# baseline (speedup 1.0000x reference)
.LBB0_17:
	s_or_b64 exec, exec, s[4:5]
	v_cmp_gt_u32_e32 vcc, 2, v190
	s_and_saveexec_b64 s[4:5], vcc
	v_lshl_add_u32 v0, v190, 2, 0
	v_add_u32_e32 v0, 0x23fc0, v0
	v_mov_b32_e32 v1, 0
	ds_write_b32 v0, v1
	s_or_b64 exec, exec, s[4:5]
	v_readfirstlane_b32 s86, v190
	s_lshr_b32 s4, s86, 6
	s_lshl_b32 s3, s2, 3
	s_add_i32 s84, s4, s3
	s_lshl_b32 s6, s82, 3
	s_cmpk_eq_i32 s82, 0x100
	v_writelane_b32 v241, s4, 42
	s_cselect_b64 s[24:25], -1, 0
	v_writelane_b32 v241, s24, 43
	s_cmpk_lg_i32 s82, 0x100
	s_mul_i32 s3, s4, 0x4100
	v_writelane_b32 v241, s25, 44
	s_cselect_b64 s[24:25], -1, 0
	s_add_i32 s36, s3, 0
	s_add_u32 s3, s80, 0x4a00000
	v_writelane_b32 v241, s3, 45
	s_addc_u32 s3, s81, 0
	v_writelane_b32 v241, s3, 46
	v_mov_b32_e32 v3, v190
	v_readlane_b32 s60, v241, 24
	v_readlane_b32 s62, v241, 26
	v_readlane_b32 s63, v241, 27
	s_cmp_lg_u64 s[62:63], 0
	s_cselect_b64 s[26:27], -1, 0
	s_add_u32 s3, s80, 0x5200000
	v_readlane_b32 s61, v241, 25
	v_readlane_b32 s64, v241, 28
	v_readlane_b32 s65, v241, 29
	v_readlane_b32 s66, v241, 30
	v_readlane_b32 s67, v241, 31
	v_readlane_b32 s68, v241, 32
	v_readlane_b32 s69, v241, 33
	v_readlane_b32 s70, v241, 34
	v_readlane_b32 s71, v241, 35
	v_readlane_b32 s72, v241, 36
	v_readlane_b32 s73, v241, 37
	v_readlane_b32 s74, v241, 38
	v_readlane_b32 s75, v241, 39
	v_writelane_b32 v241, s3, 47
	s_addc_u32 s3, s81, 0
	s_cmp_lg_u64 s[64:65], 0
	v_writelane_b32 v241, s3, 48
	s_cselect_b64 s[28:29], -1, 0
	s_add_u32 s3, s80, 0x6200000
	v_writelane_b32 v241, s3, 49
	s_addc_u32 s3, s81, 0
	v_writelane_b32 v241, s3, 50
	s_add_u32 s3, s80, 0x6a00000
	v_writelane_b32 v241, s3, 51
	s_addc_u32 s3, s81, 0
	s_cmp_lg_u64 s[66:67], 0
	v_writelane_b32 v241, s3, 52
	s_cselect_b64 s[64:65], -1, 0
	s_add_u32 s3, s80, 0x11a00000
	v_writelane_b32 v241, s3, 53
	s_addc_u32 s3, s81, 0
	s_cmp_lg_u64 s[60:61], 0
	v_writelane_b32 v241, s3, 54
	s_cselect_b64 s[30:31], -1, 0
	s_add_u32 s3, s80, 0x4200000
	v_writelane_b32 v241, s3, 55
	s_addc_u32 s3, s81, 0
	v_writelane_b32 v241, s3, 56
	s_add_u32 s3, s80, 0x200000
	v_writelane_b32 v241, s3, 57
	s_addc_u32 s3, s81, 0
	s_add_u32 s62, s80, 0x1200000
	s_addc_u32 s63, s81, 0
	s_cmp_lg_u64 s[72:73], 0
	v_writelane_b32 v241, s3, 58
	s_cselect_b64 s[34:35], -1, 0
	s_add_u32 s3, s80, 0x1600000
	v_writelane_b32 v241, s3, 59
	s_addc_u32 s3, s81, 0
	v_writelane_b32 v241, s3, 60
	s_abs_i32 s3, s6
	v_cvt_f32_u32_e32 v0, s3
	s_sub_i32 s4, 0, s3
	v_and_b32_e32 v8, 7, v3
	v_rcp_iflag_f32_e32 v0, v0
	v_bfe_u32 v2, v3, 3, 3
	v_and_b32_e32 v1, 63, v3
	v_bfe_u32 v42, v3, 4, 2
	v_mul_f32_e32 v0, 0x4f7ffffe, v0
	v_cvt_u32_f32_e32 v0, v0
	v_lshlrev_b32_e32 v3, 2, v3
	v_and_b32_e32 v4, 60, v3
	v_lshlrev_b32_e32 v30, 2, v4
	v_readfirstlane_b32 s5, v0
	v_mul_u32_u24_e32 v3, 0x104, v42
	s_mul_i32 s4, s4, s5
	v_lshlrev_b32_e32 v46, 4, v8
	v_add3_u32 v43, s36, v30, v3
	v_lshlrev_b32_e32 v44, 3, v8
	v_mul_u32_u24_e32 v3, 0x820, v8
	v_lshlrev_b32_e32 v8, 2, v2
	v_writelane_b32 v241, s36, 61
	s_mul_hi_u32 s4, s5, s4
	v_add3_u32 v45, s36, v3, v8
	v_readlane_b32 s36, v241, 0
	s_add_i32 s7, s5, s4
	v_lshlrev_b32_e32 v47, 12, v2
	s_mov_b32 s4, 0x38000
	v_mov_b32_e32 v31, 0
	v_readlane_b32 s37, v241, 1
	v_readlane_b32 s38, v241, 2
	v_readlane_b32 s39, v241, 3
	v_readlane_b32 s40, v241, 4
	v_readlane_b32 s41, v241, 5
	v_readlane_b32 s42, v241, 6
	v_readlane_b32 s43, v241, 7
	v_or3_b32 v5, v47, v46, s4
	v_lshlrev_b32_e32 v0, 10, v2
	s_mov_b32 s4, 0xe000
	s_waitcnt lgkmcnt(0)
	v_lshl_add_u64 v[6:7], s[18:19], 0, v[30:31]
	v_lshl_add_u64 v[8:9], s[20:21], 0, v[30:31]
	v_lshl_add_u64 v[10:11], s[22:23], 0, v[30:31]
	v_lshl_add_u64 v[12:13], s[36:37], 0, v[30:31]
	v_lshl_add_u64 v[14:15], s[38:39], 0, v[30:31]
	v_lshl_add_u64 v[16:17], s[40:41], 0, v[30:31]
	v_lshl_add_u64 v[18:19], s[42:43], 0, v[30:31]
	v_lshl_add_u64 v[20:21], s[14:15], 0, v[30:31]
	v_lshl_add_u64 v[22:23], s[16:17], 0, v[30:31]
	v_lshl_add_u64 v[24:25], s[68:69], 0, v[30:31]
	v_lshl_add_u64 v[26:27], s[70:71], 0, v[30:31]
	v_lshl_add_u64 v[28:29], s[74:75], 0, v[30:31]
	v_mul_u32_u24_e32 v30, 0x2c00, v2
	v_or3_b32 v48, v0, v46, s4
	v_lshlrev_b32_e32 v0, 11, v2
	s_mov_b32 s4, 0x1c000
	v_or_b32_e32 v30, v30, v46
	s_mov_b32 s15, 0
	v_or3_b32 v49, v0, v46, s4
	v_mov_b32_e32 v0, v190
	v_or_b32_e32 v50, 8, v2
	v_or_b32_e32 v51, 16, v2
	v_or_b32_e32 v52, 24, v2
	v_or_b32_e32 v53, 32, v2
	v_or_b32_e32 v54, 40, v2
	v_or_b32_e32 v55, 48, v2
	v_or_b32_e32 v56, 56, v2
	v_mov_b32_e32 v3, v31
	v_add_u32_e32 v57, 0x9a000, v30
	s_mov_b32 s19, 0x20000
	s_brev_b32 s18, -2
	v_add_u32_e32 v58, 0x410, v43
	v_add_u32_e32 v59, 0x418, v43
	v_add_u32_e32 v60, 0x820, v43
	v_add_u32_e32 v61, 0x828, v43
	v_add_u32_e32 v62, 0xc30, v43
	v_add_u32_e32 v63, 0xc38, v43
	v_mov_b32_e32 v64, 0x1800000
	s_movk_i32 s66, 0x5800
	s_movk_i32 s67, 0x3000
	s_mov_b32 s38, 0
	s_mov_b32 s20, s15
	v_cmp_lt_u32_e32 vcc, 0xff, v190
	s_nop 3
	s_cbranch_vccz .Lmy_stagger_done
	s_sleep 127
.Lmy_stagger_done:
	s_branch .LBB0_22
